# conv fix-up phase rewritten: wave-uniform scalar control, all loads of a thread's work items issued before first use
# baseline (speedup 1.0000x reference)
; __device__ __forceinline__ unsigned f2bf(float f) { unsigned u = __builtin_bit_cast(unsigned, f); return (u + 0x7fffu + ((u >> 16) & 1u)) >> 16; }
; __device__ __forceinline__ float siluf(float x) { return x * __builtin_amdgcn_rcpf(1.f + __expf(-x)); }
; __device__ __forceinline__ int otid() { int t = threadIdx.x; asm volatile("" : "+v"(t)); return t; }
; __device__ __forceinline__ void conv_phase(const Args& a, int L) {
;     const float* HB = (const float*)(a.ws + WS_U); bf16_t* act = (bf16_t*)(a.ws + WS_ACT);
;     const float* cw = a.conv_w + (size_t)L * 3 * UPW;
;     const int tid = otid(); constexpr int NTN = UPW / 256, NTILE = (M / 256) * NTN;
;     for (int idx = blockIdx.x * NTHR + tid; idx < NTILE * 256; idx += gridDim.x * NTHR) {
;         const int tile = idx >> 8, side = (idx >> 7) & 1, lc = idx & 127, pm = tile / NTN, pn = tile % NTN, ch = pn * 128 + lc;
;         const float* hb = HB + (size_t)tile * 1024;
;         float pa = hb[(2 + side) * 256 + lc], pg = hb[(2 + side) * 256 + 128 + lc];
;         if (side == 0 && (pm & 15) != 0) { const float* nb = HB + (size_t)(tile - NTN) * 1024 + 256; pa += cw[ch] * nb[lc]; pg += cw[DFF + ch] * nb[128 + lc]; }
;         if (side == 1 && (pm & 15) != 15) { const float* nb = HB + (size_t)(tile + NTN) * 1024; pa += cw[2 * UPW + ch] * nb[lc]; pg += cw[2 * UPW + DFF + ch] * nb[128 + lc]; }
;         act[(size_t)(pm * 256 + (side ? 255 : 0)) * DFF + ch] = (bf16_t)f2bf(pa * siluf(pg));
.LBB0_35:
	s_add_u32 s6, s98, 0x23300000
	v_readlane_b32 s10, v254, 45
	s_addc_u32 s7, s99, 0
	s_mul_hi_i32 s3, s10, 0x21000
	s_mul_i32 s10, s10, 0x21000
	s_add_u32 s0, s0, s10
	s_addc_u32 s1, s1, s3
	v_readlane_b32 s11, v254, 46
	v_writelane_b32 v254, s0, 53
	s_nop 1
	v_writelane_b32 v254, s1, 54
	s_nop 0
	v_readlane_b32 s0, v254, 52
	s_cmp_gt_i32 s0, 5
	s_cbranch_scc0 .LBB0_44
	s_cmp_eq_u32 s0, 6
	s_mov_b64 s[14:15], -1
	s_cbranch_scc0 .LBB0_46
	v_mov_b32_e32 v0, v206
	v_readlane_b32 s0, v253, 13
	s_nop 1
	v_add_u32_e32 v14, s0, v0
	s_mov_b32 s0, 0x58000
	v_cmp_gt_i32_e32 vcc, s0, v14
	s_and_saveexec_b64 s[10:11], vcc
	s_cbranch_execz .LBB0_45
	s_waitcnt vmcnt(0) lgkmcnt(0)
	v_and_b32_e32 v15, 0x7f, v0
	v_lshlrev_b32_e32 v2, 2, v15
	v_lshlrev_b32_e32 v3, 1, v15
	v_readfirstlane_b32 s100, v14
	v_readlane_b32 vcc_lo, v254, 53
	v_readlane_b32 vcc_hi, v254, 54
	s_mov_b32 s39, 0
	s_nop 3
	s_add_i32 s0, s100, 0x0
	s_lshr_b32 s1, s0, 8
	s_bfe_u32 s38, s0, 0x10007
	s_mul_hi_i32 s14, s1, 0x2e8ba2e9
	s_ashr_i32 s14, s14, 3
	s_mul_i32 s15, s14, 44
	s_sub_i32 s15, s1, s15
	s_lshl_b32 s28, s1, 12
	s_lshl_b32 s29, s38, 10
	s_add_i32 s28, s28, s29
	s_add_u32 s28, s6, s28
	s_addc_u32 s29, s7, 0
	global_load_dword v20, v2, s[28:29] offset:2048
	global_load_dword v21, v2, s[28:29] offset:2560
	s_and_b32 s30, s14, 15
	s_cmp_eq_u32 s38, 0
	s_cbranch_scc0 .Lcv_s1_0
	s_cmp_eq_u32 s30, 0
	s_cbranch_scc1 .Lcv_nn_0
	s_sub_u32 s28, s28, 0x2c000
	s_subb_u32 s29, s29, 0
	global_load_dword v22, v2, s[28:29] offset:1024
	global_load_dword v23, v2, s[28:29] offset:1536
	s_lshl_b32 s30, s15, 9
	s_add_u32 s30, vcc_lo, s30
	s_addc_u32 s31, vcc_hi, 0
	global_load_dword v24, v2, s[30:31]
	s_add_u32 s30, s30, 0x5800
	s_addc_u32 s31, s31, 0
	global_load_dword v25, v2, s[30:31]
	s_bitset1_b32 s39, 0
	s_branch .Lcv_nn_0
.Lcv_s1_0:
	s_cmp_eq_u32 s30, 15
	s_cbranch_scc1 .Lcv_nn_0
	s_add_u32 s28, s28, 0x2bc00
	s_addc_u32 s29, s29, 0
	global_load_dword v22, v2, s[28:29]
	global_load_dword v23, v2, s[28:29] offset:512
	s_lshl_b32 s30, s15, 9
	s_add_u32 s30, vcc_lo, s30
	s_addc_u32 s31, vcc_hi, 0
	s_add_u32 s30, s30, 0x16000
	s_addc_u32 s31, s31, 0
	global_load_dword v24, v2, s[30:31]
	s_add_u32 s30, s30, 0x5800
	s_addc_u32 s31, s31, 0
	global_load_dword v25, v2, s[30:31]
	s_bitset1_b32 s39, 0
.Lcv_nn_0:
	s_bitset1_b32 s39, 4
	s_add_i32 s0, s100, 0x20000
	s_lshr_b32 s1, s0, 8
	s_bfe_u32 s38, s0, 0x10007
	s_mul_hi_i32 s14, s1, 0x2e8ba2e9
	s_ashr_i32 s14, s14, 3
	s_mul_i32 s15, s14, 44
	s_sub_i32 s15, s1, s15
	s_lshl_b32 s28, s1, 12
	s_lshl_b32 s29, s38, 10
	s_add_i32 s28, s28, s29
	s_add_u32 s28, s6, s28
	s_addc_u32 s29, s7, 0
	global_load_dword v26, v2, s[28:29] offset:2048
	global_load_dword v27, v2, s[28:29] offset:2560
	s_and_b32 s30, s14, 15
	s_cmp_eq_u32 s38, 0
	s_cbranch_scc0 .Lcv_s1_1
	s_cmp_eq_u32 s30, 0
	s_cbranch_scc1 .Lcv_nn_1
	s_sub_u32 s28, s28, 0x2c000
	s_subb_u32 s29, s29, 0
	global_load_dword v28, v2, s[28:29] offset:1024
	global_load_dword v29, v2, s[28:29] offset:1536
	s_lshl_b32 s30, s15, 9
	s_add_u32 s30, vcc_lo, s30
	s_addc_u32 s31, vcc_hi, 0
	global_load_dword v30, v2, s[30:31]
	s_add_u32 s30, s30, 0x5800
	s_addc_u32 s31, s31, 0
	global_load_dword v31, v2, s[30:31]
	s_bitset1_b32 s39, 1
	s_branch .Lcv_nn_1
.Lcv_s1_1:
	s_cmp_eq_u32 s30, 15
	s_cbranch_scc1 .Lcv_nn_1
	s_add_u32 s28, s28, 0x2bc00
	s_addc_u32 s29, s29, 0
	global_load_dword v28, v2, s[28:29]
	global_load_dword v29, v2, s[28:29] offset:512
	s_lshl_b32 s30, s15, 9
	s_add_u32 s30, vcc_lo, s30
	s_addc_u32 s31, vcc_hi, 0
	s_add_u32 s30, s30, 0x16000
	s_addc_u32 s31, s31, 0
	global_load_dword v30, v2, s[30:31]
	s_add_u32 s30, s30, 0x5800
	s_addc_u32 s31, s31, 0
	global_load_dword v31, v2, s[30:31]
	s_bitset1_b32 s39, 1
; __device__ __forceinline__ unsigned f2bf(float f) { unsigned u = __builtin_bit_cast(unsigned, f); return (u + 0x7fffu + ((u >> 16) & 1u)) >> 16; }
; __device__ __forceinline__ float siluf(float x) { return x * __builtin_amdgcn_rcpf(1.f + __expf(-x)); }
; __device__ __forceinline__ void conv_phase(const Args& a, int L) {
;     ...
;     for (int idx = blockIdx.x * NTHR + tid; idx < NTILE * 256; idx += gridDim.x * NTHR) {
;         const int tile = idx >> 8, side = (idx >> 7) & 1, lc = idx & 127, pm = tile / NTN, pn = tile % NTN, ch = pn * 128 + lc;
;         const float* hb = HB + (size_t)tile * 1024;
;         float pa = hb[(2 + side) * 256 + lc], pg = hb[(2 + side) * 256 + 128 + lc];
;         if (side == 0 && (pm & 15) != 0) { const float* nb = HB + (size_t)(tile - NTN) * 1024 + 256; pa += cw[ch] * nb[lc]; pg += cw[DFF + ch] * nb[128 + lc]; }
;         if (side == 1 && (pm & 15) != 15) { const float* nb = HB + (size_t)(tile + NTN) * 1024; pa += cw[2 * UPW + ch] * nb[lc]; pg += cw[2 * UPW + DFF + ch] * nb[128 + lc]; }
;         act[(size_t)(pm * 256 + (side ? 255 : 0)) * DFF + ch] = (bf16_t)f2bf(pa * siluf(pg));
;     }
.Lcv_nn_1:
	s_bitset1_b32 s39, 5
	s_add_i32 s0, s100, 0x40000
	s_lshr_b32 s1, s0, 8
	s_bfe_u32 s38, s0, 0x10007
	s_mul_hi_i32 s14, s1, 0x2e8ba2e9
	s_ashr_i32 s14, s14, 3
	s_mul_i32 s15, s14, 44
	s_sub_i32 s15, s1, s15
	s_cmp_ge_u32 s0, 0x58000
	s_cbranch_scc1 .Lcv_ldone
	s_lshl_b32 s28, s1, 12
	s_lshl_b32 s29, s38, 10
	s_add_i32 s28, s28, s29
	s_add_u32 s28, s6, s28
	s_addc_u32 s29, s7, 0
	global_load_dword v32, v2, s[28:29] offset:2048
	global_load_dword v33, v2, s[28:29] offset:2560
	s_and_b32 s30, s14, 15
	s_cmp_eq_u32 s38, 0
	s_cbranch_scc0 .Lcv_s1_2
	s_cmp_eq_u32 s30, 0
	s_cbranch_scc1 .Lcv_nn_2
	s_sub_u32 s28, s28, 0x2c000
	s_subb_u32 s29, s29, 0
	global_load_dword v34, v2, s[28:29] offset:1024
	global_load_dword v35, v2, s[28:29] offset:1536
	s_lshl_b32 s30, s15, 9
	s_add_u32 s30, vcc_lo, s30
	s_addc_u32 s31, vcc_hi, 0
	global_load_dword v36, v2, s[30:31]
	s_add_u32 s30, s30, 0x5800
	s_addc_u32 s31, s31, 0
	global_load_dword v37, v2, s[30:31]
	s_bitset1_b32 s39, 2
	s_branch .Lcv_nn_2
.Lcv_s1_2:
	s_cmp_eq_u32 s30, 15
	s_cbranch_scc1 .Lcv_nn_2
	s_add_u32 s28, s28, 0x2bc00
	s_addc_u32 s29, s29, 0
	global_load_dword v34, v2, s[28:29]
	global_load_dword v35, v2, s[28:29] offset:512
	s_lshl_b32 s30, s15, 9
	s_add_u32 s30, vcc_lo, s30
	s_addc_u32 s31, vcc_hi, 0
	s_add_u32 s30, s30, 0x16000
	s_addc_u32 s31, s31, 0
	global_load_dword v36, v2, s[30:31]
	s_add_u32 s30, s30, 0x5800
	s_addc_u32 s31, s31, 0
	global_load_dword v37, v2, s[30:31]
	s_bitset1_b32 s39, 2
.Lcv_nn_2:
	s_bitset1_b32 s39, 6
.Lcv_ldone:
	s_waitcnt vmcnt(0)
	s_bitcmp1_b32 s39, 0
	s_cbranch_scc0 .Lcv_nf_0
	v_fmac_f32_e32 v20, v24, v22
	v_fmac_f32_e32 v21, v25, v23
.Lcv_nf_0:
	v_mul_f32_e32 v4, 0xbfb8aa3b, v21
	v_exp_f32_e32 v4, v4
	s_add_i32 s0, s100, 0x0
	s_lshr_b32 s1, s0, 8
	s_bfe_u32 s38, s0, 0x10007
	s_mul_hi_i32 s14, s1, 0x2e8ba2e9
	s_ashr_i32 s14, s14, 3
	s_mul_i32 s15, s14, 44
	s_sub_i32 s15, s1, s15
	v_add_f32_e32 v4, 1.0, v4
	v_rcp_f32_e32 v4, v4
	s_lshl_b32 s28, s14, 8
	s_mul_i32 s29, s38, 0xff
	s_add_i32 s28, s28, s29
	v_mul_f32_e32 v4, v21, v4
	v_mul_f32_e32 v4, v20, v4
	s_mul_i32 s28, s28, 0x2c00
	s_lshl_b32 s29, s15, 8
	v_bfe_u32 v5, v4, 16, 1
	s_add_i32 s28, s28, s29
	v_add3_u32 v4, v4, v5, s91
	s_add_u32 s28, s12, s28
	s_addc_u32 s29, s13, 0
	global_store_short_d16_hi v3, v4, s[28:29]
	s_bitcmp1_b32 s39, 1
	s_cbranch_scc0 .Lcv_nf_1
	v_fmac_f32_e32 v26, v30, v28
	v_fmac_f32_e32 v27, v31, v29
.Lcv_nf_1:
	v_mul_f32_e32 v4, 0xbfb8aa3b, v27
	v_exp_f32_e32 v4, v4
	s_add_i32 s0, s100, 0x20000
	s_lshr_b32 s1, s0, 8
	s_bfe_u32 s38, s0, 0x10007
	s_mul_hi_i32 s14, s1, 0x2e8ba2e9
	s_ashr_i32 s14, s14, 3
	s_mul_i32 s15, s14, 44
	s_sub_i32 s15, s1, s15
	v_add_f32_e32 v4, 1.0, v4
	v_rcp_f32_e32 v4, v4
	s_lshl_b32 s28, s14, 8
	s_mul_i32 s29, s38, 0xff
	s_add_i32 s28, s28, s29
	v_mul_f32_e32 v4, v27, v4
	v_mul_f32_e32 v4, v26, v4
	s_mul_i32 s28, s28, 0x2c00
	s_lshl_b32 s29, s15, 8
	v_bfe_u32 v5, v4, 16, 1
	s_add_i32 s28, s28, s29
	v_add3_u32 v4, v4, v5, s91
	s_add_u32 s28, s12, s28
	s_addc_u32 s29, s13, 0
	global_store_short_d16_hi v3, v4, s[28:29]
	s_bitcmp1_b32 s39, 6
	s_cbranch_scc0 .Lcv_done
	s_bitcmp1_b32 s39, 2
	s_cbranch_scc0 .Lcv_nf_2
	v_fmac_f32_e32 v32, v36, v34
	v_fmac_f32_e32 v33, v37, v35
.Lcv_nf_2:
	v_mul_f32_e32 v4, 0xbfb8aa3b, v33
	v_exp_f32_e32 v4, v4
	s_add_i32 s0, s100, 0x40000
	s_lshr_b32 s1, s0, 8
	s_bfe_u32 s38, s0, 0x10007
	s_mul_hi_i32 s14, s1, 0x2e8ba2e9
	s_ashr_i32 s14, s14, 3
	s_mul_i32 s15, s14, 44
	s_sub_i32 s15, s1, s15
	v_add_f32_e32 v4, 1.0, v4
	v_rcp_f32_e32 v4, v4
	s_lshl_b32 s28, s14, 8
	s_mul_i32 s29, s38, 0xff
	s_add_i32 s28, s28, s29
	v_mul_f32_e32 v4, v33, v4
	v_mul_f32_e32 v4, v32, v4
	s_mul_i32 s28, s28, 0x2c00
	s_lshl_b32 s29, s15, 8
	v_bfe_u32 v5, v4, 16, 1
	s_add_i32 s28, s28, s29
	v_add3_u32 v4, v4, v5, s91
	s_add_u32 s28, s12, s28
	s_addc_u32 s29, s13, 0
	global_store_short_d16_hi v3, v4, s[28:29]
.Lcv_done:
	s_branch .LBB0_45
.LBB0_44:
	s_cbranch_execnz .LBB0_47
	s_branch .LBB0_69
